# tile boundary: epilogue start waits vmcnt(8) (next tile's stage loads stay in flight); up-projection row statistics kept in registers, no per-tile reload at 256 workgroups
# speedup vs baseline: 1.0122x; 1.0030x over previous
.LBB0_382:
	s_waitcnt vmcnt(8)
	v_lshl_or_b32 v144, s29, 7, v156
	v_lshl_add_u32 v164, s28, 8, v1
	v_ashrrev_i32_e32 v145, 31, v144
	v_mov_b64_e32 v[142:143], s[82:83]
	s_movk_i32 s21, 0x1600
	v_mad_i64_i32 v[146:147], s[28:29], v164, s21, v[142:143]
	v_lshlrev_b64 v[144:145], 1, v[144:145]
	v_lshl_add_u64 v[146:147], v[146:147], 0, v[144:145]
	s_andn2_b64 vcc, exec, s[6:7]
	v_cvt_f32_u32_e32 v168, v166
	v_fmamk_f32 v170, v168, 0x34800000, v228
	v_rsq_f32_e32 v168, v170
	v_pk_mul_f32 v[122:123], v[126:127], v[122:123]
	v_pk_mul_f32 v[124:125], v[128:129], v[124:125]
	v_pk_mul_f32 v[114:115], v[118:119], v[114:115]
	v_pk_mul_f32 v[116:117], v[120:121], v[116:117]
	v_mul_f32_e32 v172, 0xbfb8aa3b, v168
	v_pk_mul_f32 v[126:127], v[126:127], v[172:173] op_sel_hi:[1,0]
	v_pk_mul_f32 v[128:129], v[128:129], v[172:173] op_sel_hi:[1,0]
	v_pk_mul_f32 v[118:119], v[118:119], v[172:173] op_sel_hi:[1,0]
	v_pk_mul_f32 v[120:121], v[120:121], v[172:173] op_sel_hi:[1,0]
	v_exp_f32_e32 v126, v126
	v_exp_f32_e32 v127, v127
	v_exp_f32_e32 v128, v128
	v_exp_f32_e32 v129, v129
	v_exp_f32_e32 v118, v118
	v_exp_f32_e32 v119, v119
	v_exp_f32_e32 v120, v120
	v_exp_f32_e32 v121, v121
	v_pk_fma_f32 v[126:127], v[126:127], v[170:171], v[170:171] op_sel_hi:[1,0,0]
	v_pk_fma_f32 v[128:129], v[128:129], v[170:171], v[170:171] op_sel_hi:[1,0,0]
	v_pk_fma_f32 v[118:119], v[118:119], v[170:171], v[170:171] op_sel_hi:[1,0,0]
	v_pk_fma_f32 v[120:121], v[120:121], v[170:171], v[170:171] op_sel_hi:[1,0,0]
	v_rcp_f32_e32 v126, v126
	v_rcp_f32_e32 v127, v127
	v_rcp_f32_e32 v128, v128
	v_rcp_f32_e32 v129, v129
	v_rcp_f32_e32 v118, v118
	v_rcp_f32_e32 v119, v119
	v_rcp_f32_e32 v120, v120
	v_rcp_f32_e32 v121, v121
	v_pk_mul_f32 v[122:123], v[122:123], v[126:127]
	v_pk_mul_f32 v[124:125], v[124:125], v[128:129]
	v_pk_mul_f32 v[118:119], v[114:115], v[118:119]
	v_pk_mul_f32 v[120:121], v[116:117], v[120:121]
	v_cvt_pk_bf16_f32 v114, v122, v123
	v_cvt_pk_bf16_f32 v115, v124, v125
	v_cvt_pk_bf16_f32 v116, v118, v119
	v_cvt_pk_bf16_f32 v117, v120, v121
	global_store_dwordx4 v[146:147], v[114:117], off sc1
	s_nop 1
	v_cvt_f32_u32_e32 v168, v165
	v_fmamk_f32 v170, v168, 0x34800000, v228
	v_rsq_f32_e32 v168, v170
	v_pk_mul_f32 v[106:107], v[110:111], v[106:107]
	v_pk_mul_f32 v[108:109], v[112:113], v[108:109]
	v_pk_mul_f32 v[98:99], v[102:103], v[98:99]
	v_pk_mul_f32 v[100:101], v[104:105], v[100:101]
	v_mul_f32_e32 v172, 0xbfb8aa3b, v168
	v_pk_mul_f32 v[110:111], v[110:111], v[172:173] op_sel_hi:[1,0]
	v_pk_mul_f32 v[112:113], v[112:113], v[172:173] op_sel_hi:[1,0]
	v_pk_mul_f32 v[102:103], v[102:103], v[172:173] op_sel_hi:[1,0]
	v_pk_mul_f32 v[104:105], v[104:105], v[172:173] op_sel_hi:[1,0]
	v_exp_f32_e32 v110, v110
	v_exp_f32_e32 v111, v111
	v_exp_f32_e32 v112, v112
	v_exp_f32_e32 v113, v113
	v_exp_f32_e32 v102, v102
	v_exp_f32_e32 v103, v103
	v_exp_f32_e32 v104, v104
	v_exp_f32_e32 v105, v105
	v_or_b32_e32 v114, 16, v164
	v_mad_i64_i32 v[114:115], s[28:29], v114, s21, v[142:143]
	v_lshl_add_u64 v[114:115], v[114:115], 0, v[144:145]
	v_pk_fma_f32 v[110:111], v[110:111], v[170:171], v[170:171] op_sel_hi:[1,0,0]
	v_pk_fma_f32 v[112:113], v[112:113], v[170:171], v[170:171] op_sel_hi:[1,0,0]
	v_pk_fma_f32 v[102:103], v[102:103], v[170:171], v[170:171] op_sel_hi:[1,0,0]
	v_pk_fma_f32 v[104:105], v[104:105], v[170:171], v[170:171] op_sel_hi:[1,0,0]
	v_rcp_f32_e32 v110, v110
	v_rcp_f32_e32 v111, v111
	v_rcp_f32_e32 v112, v112
	v_rcp_f32_e32 v113, v113
	v_rcp_f32_e32 v102, v102
	v_rcp_f32_e32 v103, v103
	v_rcp_f32_e32 v104, v104
	v_rcp_f32_e32 v105, v105
	v_pk_mul_f32 v[106:107], v[106:107], v[110:111]
	v_pk_mul_f32 v[108:109], v[108:109], v[112:113]
	v_pk_mul_f32 v[102:103], v[98:99], v[102:103]
	v_pk_mul_f32 v[104:105], v[100:101], v[104:105]
	v_cvt_pk_bf16_f32 v98, v106, v107
	v_cvt_pk_bf16_f32 v99, v108, v109
	v_cvt_pk_bf16_f32 v100, v102, v103
	v_cvt_pk_bf16_f32 v101, v104, v105
	global_store_dwordx4 v[114:115], v[98:101], off sc1
	s_nop 1
	v_cvt_f32_u32_e32 v168, v163
	v_fmamk_f32 v170, v168, 0x34800000, v228
	v_rsq_f32_e32 v168, v170
	v_pk_mul_f32 v[90:91], v[94:95], v[90:91]
	v_pk_mul_f32 v[92:93], v[96:97], v[92:93]
	v_pk_mul_f32 v[82:83], v[86:87], v[82:83]
	v_pk_mul_f32 v[84:85], v[88:89], v[84:85]
	v_mul_f32_e32 v172, 0xbfb8aa3b, v168
	v_pk_mul_f32 v[94:95], v[94:95], v[172:173] op_sel_hi:[1,0]
	v_pk_mul_f32 v[96:97], v[96:97], v[172:173] op_sel_hi:[1,0]
	v_pk_mul_f32 v[86:87], v[86:87], v[172:173] op_sel_hi:[1,0]
	v_pk_mul_f32 v[88:89], v[88:89], v[172:173] op_sel_hi:[1,0]
	v_exp_f32_e32 v94, v94
	v_exp_f32_e32 v95, v95
	v_exp_f32_e32 v96, v96
	v_exp_f32_e32 v97, v97
	v_exp_f32_e32 v86, v86
	v_exp_f32_e32 v87, v87
	v_exp_f32_e32 v88, v88
	v_exp_f32_e32 v89, v89
	v_or_b32_e32 v98, 32, v164
	v_mad_i64_i32 v[98:99], s[28:29], v98, s21, v[142:143]
	v_lshl_add_u64 v[98:99], v[98:99], 0, v[144:145]
	v_pk_fma_f32 v[94:95], v[94:95], v[170:171], v[170:171] op_sel_hi:[1,0,0]
	v_pk_fma_f32 v[96:97], v[96:97], v[170:171], v[170:171] op_sel_hi:[1,0,0]
	v_pk_fma_f32 v[86:87], v[86:87], v[170:171], v[170:171] op_sel_hi:[1,0,0]
	v_pk_fma_f32 v[88:89], v[88:89], v[170:171], v[170:171] op_sel_hi:[1,0,0]
	v_rcp_f32_e32 v94, v94
	v_rcp_f32_e32 v95, v95
	v_rcp_f32_e32 v96, v96
	v_rcp_f32_e32 v97, v97
	v_rcp_f32_e32 v86, v86
	v_rcp_f32_e32 v87, v87
	v_rcp_f32_e32 v88, v88
	v_rcp_f32_e32 v89, v89
	v_pk_mul_f32 v[90:91], v[90:91], v[94:95]
	v_pk_mul_f32 v[92:93], v[92:93], v[96:97]
	v_pk_mul_f32 v[86:87], v[82:83], v[86:87]
	v_pk_mul_f32 v[88:89], v[84:85], v[88:89]
	v_cvt_pk_bf16_f32 v82, v90, v91
	v_cvt_pk_bf16_f32 v83, v92, v93
	v_cvt_pk_bf16_f32 v84, v86, v87
	v_cvt_pk_bf16_f32 v85, v88, v89
	global_store_dwordx4 v[98:99], v[82:85], off sc1
	s_nop 1
	v_cvt_f32_u32_e32 v168, v162
	v_fmamk_f32 v170, v168, 0x34800000, v228
	v_rsq_f32_e32 v168, v170
	v_pk_mul_f32 v[74:75], v[78:79], v[74:75]
	v_pk_mul_f32 v[76:77], v[80:81], v[76:77]
	v_pk_mul_f32 v[66:67], v[70:71], v[66:67]
	v_pk_mul_f32 v[68:69], v[72:73], v[68:69]
	v_mul_f32_e32 v172, 0xbfb8aa3b, v168
	v_pk_mul_f32 v[78:79], v[78:79], v[172:173] op_sel_hi:[1,0]
	v_pk_mul_f32 v[80:81], v[80:81], v[172:173] op_sel_hi:[1,0]
	v_pk_mul_f32 v[70:71], v[70:71], v[172:173] op_sel_hi:[1,0]
	v_pk_mul_f32 v[72:73], v[72:73], v[172:173] op_sel_hi:[1,0]
	v_exp_f32_e32 v78, v78
	v_exp_f32_e32 v79, v79
	v_exp_f32_e32 v80, v80
	v_exp_f32_e32 v81, v81
	v_exp_f32_e32 v70, v70
	v_exp_f32_e32 v71, v71
	v_exp_f32_e32 v72, v72
	v_exp_f32_e32 v73, v73
	v_or_b32_e32 v82, 48, v164
	v_mad_i64_i32 v[82:83], s[28:29], v82, s21, v[142:143]
	v_lshl_add_u64 v[82:83], v[82:83], 0, v[144:145]
	v_pk_fma_f32 v[78:79], v[78:79], v[170:171], v[170:171] op_sel_hi:[1,0,0]
	v_pk_fma_f32 v[80:81], v[80:81], v[170:171], v[170:171] op_sel_hi:[1,0,0]
	v_pk_fma_f32 v[70:71], v[70:71], v[170:171], v[170:171] op_sel_hi:[1,0,0]
	v_pk_fma_f32 v[72:73], v[72:73], v[170:171], v[170:171] op_sel_hi:[1,0,0]
	v_rcp_f32_e32 v78, v78
	v_rcp_f32_e32 v79, v79
	v_rcp_f32_e32 v80, v80
	v_rcp_f32_e32 v81, v81
	v_rcp_f32_e32 v70, v70
	v_rcp_f32_e32 v71, v71
	v_rcp_f32_e32 v72, v72
	v_rcp_f32_e32 v73, v73
	v_pk_mul_f32 v[74:75], v[74:75], v[78:79]
	v_pk_mul_f32 v[76:77], v[76:77], v[80:81]
	v_pk_mul_f32 v[70:71], v[66:67], v[70:71]
	v_pk_mul_f32 v[72:73], v[68:69], v[72:73]
	v_cvt_pk_bf16_f32 v66, v74, v75
	v_cvt_pk_bf16_f32 v67, v76, v77
	v_cvt_pk_bf16_f32 v68, v70, v71
	v_cvt_pk_bf16_f32 v69, v72, v73
	global_store_dwordx4 v[82:83], v[66:69], off sc1
	s_nop 1
	v_cvt_f32_u32_e32 v168, v161
	v_fmamk_f32 v170, v168, 0x34800000, v228
	v_rsq_f32_e32 v168, v170
	v_pk_mul_f32 v[58:59], v[62:63], v[58:59]
	v_pk_mul_f32 v[60:61], v[64:65], v[60:61]
	v_pk_mul_f32 v[50:51], v[54:55], v[50:51]
	v_pk_mul_f32 v[52:53], v[56:57], v[52:53]
	v_mul_f32_e32 v172, 0xbfb8aa3b, v168
	v_pk_mul_f32 v[62:63], v[62:63], v[172:173] op_sel_hi:[1,0]
	v_pk_mul_f32 v[64:65], v[64:65], v[172:173] op_sel_hi:[1,0]
	v_pk_mul_f32 v[54:55], v[54:55], v[172:173] op_sel_hi:[1,0]
	v_pk_mul_f32 v[56:57], v[56:57], v[172:173] op_sel_hi:[1,0]
	v_exp_f32_e32 v62, v62
	v_exp_f32_e32 v63, v63
	v_exp_f32_e32 v64, v64
	v_exp_f32_e32 v65, v65
	v_exp_f32_e32 v54, v54
	v_exp_f32_e32 v55, v55
	v_exp_f32_e32 v56, v56
	v_exp_f32_e32 v57, v57
	v_add_u32_e32 v66, 0x80, v164
	v_mad_i64_i32 v[66:67], s[28:29], v66, s21, v[142:143]
	v_lshl_add_u64 v[66:67], v[66:67], 0, v[144:145]
	v_pk_fma_f32 v[62:63], v[62:63], v[170:171], v[170:171] op_sel_hi:[1,0,0]
	v_pk_fma_f32 v[64:65], v[64:65], v[170:171], v[170:171] op_sel_hi:[1,0,0]
	v_pk_fma_f32 v[54:55], v[54:55], v[170:171], v[170:171] op_sel_hi:[1,0,0]
	v_pk_fma_f32 v[56:57], v[56:57], v[170:171], v[170:171] op_sel_hi:[1,0,0]
	v_rcp_f32_e32 v62, v62
	v_rcp_f32_e32 v63, v63
	v_rcp_f32_e32 v64, v64
	v_rcp_f32_e32 v65, v65
	v_rcp_f32_e32 v54, v54
	v_rcp_f32_e32 v55, v55
	v_rcp_f32_e32 v56, v56
	v_rcp_f32_e32 v57, v57
	v_pk_mul_f32 v[58:59], v[58:59], v[62:63]
	v_pk_mul_f32 v[60:61], v[60:61], v[64:65]
	v_pk_mul_f32 v[54:55], v[50:51], v[54:55]
	v_pk_mul_f32 v[56:57], v[52:53], v[56:57]
	v_cvt_pk_bf16_f32 v50, v58, v59
	v_cvt_pk_bf16_f32 v51, v60, v61
	v_cvt_pk_bf16_f32 v52, v54, v55
	v_cvt_pk_bf16_f32 v53, v56, v57
	global_store_dwordx4 v[66:67], v[50:53], off sc1
	s_nop 1
	v_cvt_f32_u32_e32 v168, v160
	v_fmamk_f32 v170, v168, 0x34800000, v228
	v_rsq_f32_e32 v168, v170
	v_pk_mul_f32 v[42:43], v[46:47], v[42:43]
	v_pk_mul_f32 v[44:45], v[48:49], v[44:45]
	v_pk_mul_f32 v[34:35], v[38:39], v[34:35]
	v_pk_mul_f32 v[36:37], v[40:41], v[36:37]
	v_mul_f32_e32 v172, 0xbfb8aa3b, v168
	v_pk_mul_f32 v[46:47], v[46:47], v[172:173] op_sel_hi:[1,0]
	v_pk_mul_f32 v[48:49], v[48:49], v[172:173] op_sel_hi:[1,0]
	v_pk_mul_f32 v[38:39], v[38:39], v[172:173] op_sel_hi:[1,0]
	v_pk_mul_f32 v[40:41], v[40:41], v[172:173] op_sel_hi:[1,0]
	v_exp_f32_e32 v46, v46
	v_exp_f32_e32 v47, v47
	v_exp_f32_e32 v48, v48
	v_exp_f32_e32 v49, v49
	v_exp_f32_e32 v38, v38
	v_exp_f32_e32 v39, v39
	v_exp_f32_e32 v40, v40
	v_exp_f32_e32 v41, v41
	v_add_u32_e32 v50, 0x90, v164
	v_mad_i64_i32 v[50:51], s[28:29], v50, s21, v[142:143]
	v_lshl_add_u64 v[50:51], v[50:51], 0, v[144:145]
	v_pk_fma_f32 v[46:47], v[46:47], v[170:171], v[170:171] op_sel_hi:[1,0,0]
	v_pk_fma_f32 v[48:49], v[48:49], v[170:171], v[170:171] op_sel_hi:[1,0,0]
	v_pk_fma_f32 v[38:39], v[38:39], v[170:171], v[170:171] op_sel_hi:[1,0,0]
	v_pk_fma_f32 v[40:41], v[40:41], v[170:171], v[170:171] op_sel_hi:[1,0,0]
	v_rcp_f32_e32 v46, v46
	v_rcp_f32_e32 v47, v47
	v_rcp_f32_e32 v48, v48
	v_rcp_f32_e32 v49, v49
	v_rcp_f32_e32 v38, v38
	v_rcp_f32_e32 v39, v39
	v_rcp_f32_e32 v40, v40
	v_rcp_f32_e32 v41, v41
	v_pk_mul_f32 v[42:43], v[42:43], v[46:47]
	v_pk_mul_f32 v[44:45], v[44:45], v[48:49]
	v_pk_mul_f32 v[38:39], v[34:35], v[38:39]
	v_pk_mul_f32 v[40:41], v[36:37], v[40:41]
	v_cvt_pk_bf16_f32 v34, v42, v43
	v_cvt_pk_bf16_f32 v35, v44, v45
	v_cvt_pk_bf16_f32 v36, v38, v39
	v_cvt_pk_bf16_f32 v37, v40, v41
	global_store_dwordx4 v[50:51], v[34:37], off sc1
	s_nop 1
	v_cvt_f32_u32_e32 v168, v159
	v_fmamk_f32 v170, v168, 0x34800000, v228
	v_rsq_f32_e32 v168, v170
	v_pk_mul_f32 v[26:27], v[30:31], v[26:27]
	v_pk_mul_f32 v[28:29], v[32:33], v[28:29]
	v_pk_mul_f32 v[18:19], v[22:23], v[18:19]
	v_pk_mul_f32 v[20:21], v[24:25], v[20:21]
	v_mul_f32_e32 v172, 0xbfb8aa3b, v168
	v_pk_mul_f32 v[30:31], v[30:31], v[172:173] op_sel_hi:[1,0]
	v_pk_mul_f32 v[32:33], v[32:33], v[172:173] op_sel_hi:[1,0]
	v_pk_mul_f32 v[22:23], v[22:23], v[172:173] op_sel_hi:[1,0]
	v_pk_mul_f32 v[24:25], v[24:25], v[172:173] op_sel_hi:[1,0]
	v_exp_f32_e32 v30, v30
	v_exp_f32_e32 v31, v31
	v_exp_f32_e32 v32, v32
	v_exp_f32_e32 v33, v33
	v_exp_f32_e32 v22, v22
	v_exp_f32_e32 v23, v23
	v_exp_f32_e32 v24, v24
	v_exp_f32_e32 v25, v25
	v_add_u32_e32 v34, 0xa0, v164
	v_mad_i64_i32 v[34:35], s[28:29], v34, s21, v[142:143]
	v_lshl_add_u64 v[34:35], v[34:35], 0, v[144:145]
	v_pk_fma_f32 v[30:31], v[30:31], v[170:171], v[170:171] op_sel_hi:[1,0,0]
	v_pk_fma_f32 v[32:33], v[32:33], v[170:171], v[170:171] op_sel_hi:[1,0,0]
	v_pk_fma_f32 v[22:23], v[22:23], v[170:171], v[170:171] op_sel_hi:[1,0,0]
	v_pk_fma_f32 v[24:25], v[24:25], v[170:171], v[170:171] op_sel_hi:[1,0,0]
	v_rcp_f32_e32 v30, v30
	v_rcp_f32_e32 v31, v31
	v_rcp_f32_e32 v32, v32
	v_rcp_f32_e32 v33, v33
	v_rcp_f32_e32 v22, v22
	v_rcp_f32_e32 v23, v23
	v_rcp_f32_e32 v24, v24
	v_rcp_f32_e32 v25, v25
	v_pk_mul_f32 v[26:27], v[26:27], v[30:31]
	v_pk_mul_f32 v[28:29], v[28:29], v[32:33]
	v_pk_mul_f32 v[22:23], v[18:19], v[22:23]
	v_pk_mul_f32 v[24:25], v[20:21], v[24:25]
	v_cvt_pk_bf16_f32 v18, v26, v27
	v_cvt_pk_bf16_f32 v19, v28, v29
	v_cvt_pk_bf16_f32 v20, v22, v23
	v_cvt_pk_bf16_f32 v21, v24, v25
	global_store_dwordx4 v[34:35], v[18:21], off sc1
	s_nop 1
	v_cvt_f32_u32_e32 v168, v158
	v_fmamk_f32 v170, v168, 0x34800000, v228
	v_rsq_f32_e32 v168, v170
	v_pk_mul_f32 v[10:11], v[14:15], v[10:11]
	v_pk_mul_f32 v[12:13], v[16:17], v[12:13]
	v_pk_mul_f32 v[2:3], v[6:7], v[2:3]
	v_pk_mul_f32 v[4:5], v[8:9], v[4:5]
	v_mul_f32_e32 v172, 0xbfb8aa3b, v168
	v_pk_mul_f32 v[14:15], v[14:15], v[172:173] op_sel_hi:[1,0]
	v_pk_mul_f32 v[16:17], v[16:17], v[172:173] op_sel_hi:[1,0]
	v_pk_mul_f32 v[6:7], v[6:7], v[172:173] op_sel_hi:[1,0]
	v_pk_mul_f32 v[8:9], v[8:9], v[172:173] op_sel_hi:[1,0]
	v_exp_f32_e32 v14, v14
	v_exp_f32_e32 v15, v15
	v_exp_f32_e32 v16, v16
	v_exp_f32_e32 v17, v17
	v_exp_f32_e32 v6, v6
	v_exp_f32_e32 v7, v7
	v_exp_f32_e32 v8, v8
	v_exp_f32_e32 v9, v9
	v_add_u32_e32 v18, 0xb0, v164
	v_mad_i64_i32 v[18:19], s[28:29], v18, s21, v[142:143]
	v_lshl_add_u64 v[18:19], v[18:19], 0, v[144:145]
	v_pk_fma_f32 v[14:15], v[14:15], v[170:171], v[170:171] op_sel_hi:[1,0,0]
	v_pk_fma_f32 v[16:17], v[16:17], v[170:171], v[170:171] op_sel_hi:[1,0,0]
	v_pk_fma_f32 v[6:7], v[6:7], v[170:171], v[170:171] op_sel_hi:[1,0,0]
	v_pk_fma_f32 v[8:9], v[8:9], v[170:171], v[170:171] op_sel_hi:[1,0,0]
	v_rcp_f32_e32 v14, v14
	v_rcp_f32_e32 v15, v15
	v_rcp_f32_e32 v16, v16
	v_rcp_f32_e32 v17, v17
	v_rcp_f32_e32 v6, v6
	v_rcp_f32_e32 v7, v7
	v_rcp_f32_e32 v8, v8
	v_rcp_f32_e32 v9, v9
	v_pk_mul_f32 v[10:11], v[10:11], v[14:15]
	v_pk_mul_f32 v[12:13], v[12:13], v[16:17]
	v_pk_mul_f32 v[6:7], v[2:3], v[6:7]
	v_pk_mul_f32 v[8:9], v[4:5], v[8:9]
	v_cvt_pk_bf16_f32 v2, v10, v11
	v_cvt_pk_bf16_f32 v3, v12, v13
	v_cvt_pk_bf16_f32 v4, v6, v7
	v_cvt_pk_bf16_f32 v5, v8, v9
	global_store_dwordx4 v[18:19], v[2:5], off sc1
	s_nop 1
	s_mov_b64 s[28:29], -1
	s_cbranch_vccnz .LBB0_359
	s_cmpk_eq_i32 s98, 0x100
	s_cbranch_scc1 .Lsw_rsu_keep
	s_lshl_b32 s6, s22, 8
	v_add_u32_e32 v2, s6, v1
	v_ashrrev_i32_e32 v3, 31, v2
	v_lshl_add_u64 v[2:3], v[2:3], 2, s[12:13]
	global_load_dword v166, v[2:3], off
	v_add_u32_e32 v2, s6, v148
	v_ashrrev_i32_e32 v3, 31, v2
	v_lshl_add_u64 v[2:3], v[2:3], 2, s[12:13]
	global_load_dword v165, v[2:3], off
	v_add_u32_e32 v2, s6, v149
	v_ashrrev_i32_e32 v3, 31, v2
	v_lshl_add_u64 v[2:3], v[2:3], 2, s[12:13]
	global_load_dword v163, v[2:3], off
	v_add_u32_e32 v2, s6, v150
	v_ashrrev_i32_e32 v3, 31, v2
	v_lshl_add_u64 v[2:3], v[2:3], 2, s[12:13]
	global_load_dword v162, v[2:3], off
	v_add_u32_e32 v2, s6, v151
	v_ashrrev_i32_e32 v3, 31, v2
	v_lshl_add_u64 v[2:3], v[2:3], 2, s[12:13]
	global_load_dword v161, v[2:3], off
	v_add_u32_e32 v2, s6, v152
	v_ashrrev_i32_e32 v3, 31, v2
	v_lshl_add_u64 v[2:3], v[2:3], 2, s[12:13]
	global_load_dword v160, v[2:3], off
	v_add_u32_e32 v2, s6, v153
	v_ashrrev_i32_e32 v3, 31, v2
	v_lshl_add_u64 v[2:3], v[2:3], 2, s[12:13]
	global_load_dword v159, v[2:3], off
	v_add_u32_e32 v2, s6, v154
	v_ashrrev_i32_e32 v3, 31, v2
	v_lshl_add_u64 v[2:3], v[2:3], 2, s[12:13]
	global_load_dword v158, v[2:3], off
.Lsw_rsu_keep:
	s_andn2_b64 vcc, exec, s[14:15]
	s_cbranch_vccnz .LBB0_358
	s_barrier
	s_branch .LBB0_358

.LBB0_476:
	s_add_i32 s63, s31, 2
	s_add_u32 s38, s28, s36
	s_addc_u32 s39, s29, s37
	s_add_u32 s64, s26, s36
	s_addc_u32 s65, s27, s37
	s_add_i32 s66, 0, 0x10000
	s_cmp_eq_u32 s59, s31
	s_cselect_b32 s39, s9, s39
	s_cselect_b32 s38, s8, s38
	s_cselect_b32 s65, s35, s65
	s_cselect_b32 s64, s34, s64
	s_add_i32 s31, 0, 0x14000
	v_add_u32_e32 v160, s66, v146
	v_add_u32_e32 v176, s31, v146
	ds_read_b128 v[148:151], v160
	ds_read_b128 v[152:155], v160 offset:1024
	ds_read_b128 v[156:159], v160 offset:2048
	ds_read_b128 v[160:163], v160 offset:3072
	ds_read_b128 v[164:167], v176
	ds_read_b128 v[168:171], v176 offset:1024
	ds_read_b128 v[172:175], v176 offset:2048
	ds_read_b128 v[176:179], v176 offset:3072
	v_lshl_add_u64 v[208:209], s[28:29], 0, v[142:143]
	s_add_i32 m0, s51, 0xc000
	ds_read_b128 v[180:183], v147
	ds_read_b128 v[184:187], v147 offset:1024
	ds_read_b128 v[188:191], v147 offset:2048
	ds_read_b128 v[192:195], v147 offset:3072
	ds_read_b128 v[196:199], v147 offset:4096
	ds_read_b128 v[200:203], v147 offset:5120
	ds_read_b128 v[204:207], v147 offset:6144
	ds_read_b128 v[220:223], v147 offset:7168
	global_load_lds_dwordx4 v[208:209], off
	v_lshl_add_u64 v[208:209], s[28:29], 0, v[144:145]
	s_add_i32 m0, s51, 0xe000
	s_nop 0
	global_load_lds_dwordx4 v[208:209], off
	s_nop 0
	s_nop 0
	s_nop 0
	s_nop 0
	s_nop 0
	s_nop 0
	s_nop 0
	s_nop 0
	s_nop 0
	s_nop 0
	s_nop 0
	s_nop 0
	s_nop 0
	s_nop 0
	s_nop 0
	s_nop 0
	s_nop 0
	s_nop 0
	s_nop 0
	s_nop 0
	s_nop 0
	s_nop 0
	s_nop 0
	s_nop 0
	s_nop 0
	s_nop 0
	s_nop 0
	s_nop 0
	s_waitcnt vmcnt(8)
	s_waitcnt lgkmcnt(0)
	s_barrier
	s_waitcnt lgkmcnt(0)
	v_mfma_f32_16x16x32_bf16 v[126:129], v[148:151], v[180:183], v[126:129]
	v_mfma_f32_16x16x32_bf16 v[122:125], v[156:159], v[180:183], v[122:125]
	v_mfma_f32_16x16x32_bf16 v[110:113], v[148:151], v[188:191], v[110:113]
	v_mfma_f32_16x16x32_bf16 v[106:109], v[156:159], v[188:191], v[106:109]
	v_mfma_f32_16x16x32_bf16 v[94:97], v[148:151], v[196:199], v[94:97]
	v_mfma_f32_16x16x32_bf16 v[90:93], v[156:159], v[196:199], v[90:93]
	v_mfma_f32_16x16x32_bf16 v[78:81], v[148:151], v[204:207], v[78:81]
	v_mfma_f32_16x16x32_bf16 v[74:77], v[156:159], v[204:207], v[74:77]
	v_mfma_f32_16x16x32_bf16 v[126:129], v[152:155], v[184:187], v[126:129]
	v_mfma_f32_16x16x32_bf16 v[122:125], v[160:163], v[184:187], v[122:125]
	v_mfma_f32_16x16x32_bf16 v[110:113], v[152:155], v[192:195], v[110:113]
	v_mfma_f32_16x16x32_bf16 v[106:109], v[160:163], v[192:195], v[106:109]
	v_mfma_f32_16x16x32_bf16 v[94:97], v[152:155], v[200:203], v[94:97]
	v_mfma_f32_16x16x32_bf16 v[90:93], v[160:163], v[200:203], v[90:93]
	v_mfma_f32_16x16x32_bf16 v[78:81], v[152:155], v[220:223], v[78:81]
	v_mfma_f32_16x16x32_bf16 v[74:77], v[160:163], v[220:223], v[74:77]
	v_mfma_f32_16x16x32_bf16 v[118:121], v[164:167], v[180:183], v[118:121]
	v_mfma_f32_16x16x32_bf16 v[114:117], v[172:175], v[180:183], v[114:117]
	v_mfma_f32_16x16x32_bf16 v[102:105], v[164:167], v[188:191], v[102:105]
	v_mfma_f32_16x16x32_bf16 v[98:101], v[172:175], v[188:191], v[98:101]
	v_mfma_f32_16x16x32_bf16 v[86:89], v[164:167], v[196:199], v[86:89]
	v_mfma_f32_16x16x32_bf16 v[82:85], v[172:175], v[196:199], v[82:85]
	v_mfma_f32_16x16x32_bf16 v[70:73], v[164:167], v[204:207], v[70:73]
	v_mfma_f32_16x16x32_bf16 v[66:69], v[172:175], v[204:207], v[66:69]
	v_mfma_f32_16x16x32_bf16 v[118:121], v[168:171], v[184:187], v[118:121]
	v_mfma_f32_16x16x32_bf16 v[114:117], v[176:179], v[184:187], v[114:117]
	v_mfma_f32_16x16x32_bf16 v[102:105], v[168:171], v[192:195], v[102:105]
	v_mfma_f32_16x16x32_bf16 v[98:101], v[176:179], v[192:195], v[98:101]
	v_mfma_f32_16x16x32_bf16 v[86:89], v[168:171], v[200:203], v[86:89]
	v_mfma_f32_16x16x32_bf16 v[82:85], v[176:179], v[200:203], v[82:85]
	v_mfma_f32_16x16x32_bf16 v[70:73], v[168:171], v[220:223], v[70:73]
	v_mfma_f32_16x16x32_bf16 v[66:69], v[176:179], v[220:223], v[66:69]
	s_barrier
	s_add_i32 s66, s66, s47
	v_lshl_add_u64 v[208:209], s[64:65], 0, v[132:133]
	s_mov_b32 m0, s66
	ds_read_b128 v[180:183], v147 offset:16384
	ds_read_b128 v[184:187], v147 offset:17408
	ds_read_b128 v[188:191], v147 offset:18432
	ds_read_b128 v[192:195], v147 offset:19456
	ds_read_b128 v[196:199], v147 offset:20480
	ds_read_b128 v[200:203], v147 offset:21504
	ds_read_b128 v[204:207], v147 offset:22528
	ds_read_b128 v[220:223], v147 offset:23552
	global_load_lds_dwordx4 v[208:209], off
	s_add_i32 m0, s66, 0x2000
	v_lshl_add_u64 v[224:225], s[64:65], 0, v[136:137]
	s_add_u32 s64, s64, s45
	s_addc_u32 s65, s65, 0
	s_add_i32 s31, s31, s47
	global_load_lds_dwordx4 v[224:225], off
	v_lshl_add_u64 v[230:231], s[64:65], 0, v[132:133]
	s_mov_b32 m0, s31
	v_lshl_add_u64 v[236:237], s[64:65], 0, v[136:137]
	global_load_lds_dwordx4 v[230:231], off
	s_add_i32 m0, s31, 0x2000
	v_lshl_add_u64 v[238:239], s[38:39], 0, v[130:131]
	global_load_lds_dwordx4 v[236:237], off
	s_mov_b32 m0, s51
	v_lshl_add_u64 v[240:241], s[38:39], 0, v[134:135]
	global_load_lds_dwordx4 v[238:239], off
	s_mov_b32 m0, s52
	s_nop 0
	global_load_lds_dwordx4 v[240:241], off
	s_nop 0
	s_nop 0
	s_nop 0
	s_nop 0
	s_nop 0
	s_nop 0
	s_waitcnt vmcnt(8)
	s_waitcnt lgkmcnt(0)
	s_barrier
	s_waitcnt lgkmcnt(0)
	v_mfma_f32_16x16x32_bf16 v[62:65], v[148:151], v[180:183], v[62:65]
	v_mfma_f32_16x16x32_bf16 v[58:61], v[156:159], v[180:183], v[58:61]
	v_mfma_f32_16x16x32_bf16 v[46:49], v[148:151], v[188:191], v[46:49]
	v_mfma_f32_16x16x32_bf16 v[42:45], v[156:159], v[188:191], v[42:45]
	v_mfma_f32_16x16x32_bf16 v[30:33], v[148:151], v[196:199], v[30:33]
	v_mfma_f32_16x16x32_bf16 v[26:29], v[156:159], v[196:199], v[26:29]
	v_mfma_f32_16x16x32_bf16 v[14:17], v[148:151], v[204:207], v[14:17]
	v_mfma_f32_16x16x32_bf16 v[10:13], v[156:159], v[204:207], v[10:13]
	v_mfma_f32_16x16x32_bf16 v[62:65], v[152:155], v[184:187], v[62:65]
	v_mfma_f32_16x16x32_bf16 v[58:61], v[160:163], v[184:187], v[58:61]
	v_mfma_f32_16x16x32_bf16 v[46:49], v[152:155], v[192:195], v[46:49]
	v_mfma_f32_16x16x32_bf16 v[42:45], v[160:163], v[192:195], v[42:45]
	v_mfma_f32_16x16x32_bf16 v[30:33], v[152:155], v[200:203], v[30:33]
	v_mfma_f32_16x16x32_bf16 v[26:29], v[160:163], v[200:203], v[26:29]
	v_mfma_f32_16x16x32_bf16 v[14:17], v[152:155], v[220:223], v[14:17]
	v_mfma_f32_16x16x32_bf16 v[10:13], v[160:163], v[220:223], v[10:13]
	v_mfma_f32_16x16x32_bf16 v[54:57], v[164:167], v[180:183], v[54:57]
	v_mfma_f32_16x16x32_bf16 v[50:53], v[172:175], v[180:183], v[50:53]
	v_mfma_f32_16x16x32_bf16 v[38:41], v[164:167], v[188:191], v[38:41]
	v_mfma_f32_16x16x32_bf16 v[34:37], v[172:175], v[188:191], v[34:37]
	v_mfma_f32_16x16x32_bf16 v[22:25], v[164:167], v[196:199], v[22:25]
	v_mfma_f32_16x16x32_bf16 v[18:21], v[172:175], v[196:199], v[18:21]
	v_mfma_f32_16x16x32_bf16 v[6:9], v[164:167], v[204:207], v[6:9]
	v_mfma_f32_16x16x32_bf16 v[2:5], v[172:175], v[204:207], v[2:5]
	v_mfma_f32_16x16x32_bf16 v[54:57], v[168:171], v[184:187], v[54:57]
	v_mfma_f32_16x16x32_bf16 v[50:53], v[176:179], v[184:187], v[50:53]
	v_mfma_f32_16x16x32_bf16 v[38:41], v[168:171], v[192:195], v[38:41]
	v_mfma_f32_16x16x32_bf16 v[34:37], v[176:179], v[192:195], v[34:37]
	v_mfma_f32_16x16x32_bf16 v[22:25], v[168:171], v[200:203], v[22:25]
	v_mfma_f32_16x16x32_bf16 v[18:21], v[176:179], v[200:203], v[18:21]
	v_mfma_f32_16x16x32_bf16 v[6:9], v[168:171], v[220:223], v[6:9]
	v_mfma_f32_16x16x32_bf16 v[2:5], v[176:179], v[220:223], v[2:5]
	s_barrier
	s_add_i32 s31, 0, 0x18000
	s_add_i32 s64, 0, 0x1c000
	v_add_u32_e32 v160, s31, v146
	v_add_u32_e32 v176, s64, v146
	ds_read_b128 v[148:151], v160
	ds_read_b128 v[152:155], v160 offset:1024
	ds_read_b128 v[156:159], v160 offset:2048
	ds_read_b128 v[160:163], v160 offset:3072
	ds_read_b128 v[164:167], v176
	ds_read_b128 v[168:171], v176 offset:1024
	ds_read_b128 v[172:175], v176 offset:2048
	ds_read_b128 v[176:179], v176 offset:3072
	s_add_u32 s38, s38, s45
	s_addc_u32 s39, s39, 0
	s_mov_b32 m0, s53
	v_lshl_add_u64 v[242:243], s[38:39], 0, v[130:131]
	ds_read_b128 v[180:183], v147 offset:32768
	ds_read_b128 v[184:187], v147 offset:33792
	ds_read_b128 v[188:191], v147 offset:34816
	ds_read_b128 v[192:195], v147 offset:35840
	ds_read_b128 v[196:199], v147 offset:36864
	ds_read_b128 v[200:203], v147 offset:37888
	ds_read_b128 v[204:207], v147 offset:38912
	ds_read_b128 v[220:223], v147 offset:39936
	global_load_lds_dwordx4 v[242:243], off
	v_lshl_add_u64 v[242:243], s[38:39], 0, v[134:135]
	s_mov_b32 m0, s54
	s_nop 0
	global_load_lds_dwordx4 v[242:243], off
	s_nop 0
	s_nop 0
	s_nop 0
	s_nop 0
	s_nop 0
	s_nop 0
	s_nop 0
	s_nop 0
	s_waitcnt vmcnt(8)
	s_waitcnt lgkmcnt(0)
	s_barrier
	s_waitcnt lgkmcnt(0)
	v_mfma_f32_16x16x32_bf16 v[126:129], v[148:151], v[180:183], v[126:129]
	v_mfma_f32_16x16x32_bf16 v[122:125], v[156:159], v[180:183], v[122:125]
	v_mfma_f32_16x16x32_bf16 v[110:113], v[148:151], v[188:191], v[110:113]
	v_mfma_f32_16x16x32_bf16 v[106:109], v[156:159], v[188:191], v[106:109]
	v_mfma_f32_16x16x32_bf16 v[94:97], v[148:151], v[196:199], v[94:97]
	v_mfma_f32_16x16x32_bf16 v[90:93], v[156:159], v[196:199], v[90:93]
	v_mfma_f32_16x16x32_bf16 v[78:81], v[148:151], v[204:207], v[78:81]
	v_mfma_f32_16x16x32_bf16 v[74:77], v[156:159], v[204:207], v[74:77]
	v_mfma_f32_16x16x32_bf16 v[126:129], v[152:155], v[184:187], v[126:129]
	v_mfma_f32_16x16x32_bf16 v[122:125], v[160:163], v[184:187], v[122:125]
	v_mfma_f32_16x16x32_bf16 v[110:113], v[152:155], v[192:195], v[110:113]
	v_mfma_f32_16x16x32_bf16 v[106:109], v[160:163], v[192:195], v[106:109]
	v_mfma_f32_16x16x32_bf16 v[94:97], v[152:155], v[200:203], v[94:97]
	v_mfma_f32_16x16x32_bf16 v[90:93], v[160:163], v[200:203], v[90:93]
	v_mfma_f32_16x16x32_bf16 v[78:81], v[152:155], v[220:223], v[78:81]
	v_mfma_f32_16x16x32_bf16 v[74:77], v[160:163], v[220:223], v[74:77]
	v_mfma_f32_16x16x32_bf16 v[118:121], v[164:167], v[180:183], v[118:121]
	v_mfma_f32_16x16x32_bf16 v[114:117], v[172:175], v[180:183], v[114:117]
	v_mfma_f32_16x16x32_bf16 v[102:105], v[164:167], v[188:191], v[102:105]
	v_mfma_f32_16x16x32_bf16 v[98:101], v[172:175], v[188:191], v[98:101]
	v_mfma_f32_16x16x32_bf16 v[86:89], v[164:167], v[196:199], v[86:89]
	v_mfma_f32_16x16x32_bf16 v[82:85], v[172:175], v[196:199], v[82:85]
	v_mfma_f32_16x16x32_bf16 v[70:73], v[164:167], v[204:207], v[70:73]
	v_mfma_f32_16x16x32_bf16 v[66:69], v[172:175], v[204:207], v[66:69]
	v_mfma_f32_16x16x32_bf16 v[118:121], v[168:171], v[184:187], v[118:121]
	v_mfma_f32_16x16x32_bf16 v[114:117], v[176:179], v[184:187], v[114:117]
	v_mfma_f32_16x16x32_bf16 v[102:105], v[168:171], v[192:195], v[102:105]
	v_mfma_f32_16x16x32_bf16 v[98:101], v[176:179], v[192:195], v[98:101]
	v_mfma_f32_16x16x32_bf16 v[86:89], v[168:171], v[200:203], v[86:89]
	v_mfma_f32_16x16x32_bf16 v[82:85], v[176:179], v[200:203], v[82:85]
	v_mfma_f32_16x16x32_bf16 v[70:73], v[168:171], v[220:223], v[70:73]
	v_mfma_f32_16x16x32_bf16 v[66:69], v[176:179], v[220:223], v[66:69]
	s_barrier
	s_add_i32 s31, s31, s47
	v_lshl_add_u64 v[208:209], v[208:209], 0, s[96:97]
	s_mov_b32 m0, s31
	ds_read_b128 v[180:183], v147 offset:49152
	ds_read_b128 v[184:187], v147 offset:50176
	ds_read_b128 v[188:191], v147 offset:51200
	ds_read_b128 v[192:195], v147 offset:52224
	ds_read_b128 v[196:199], v147 offset:53248
	ds_read_b128 v[200:203], v147 offset:54272
	ds_read_b128 v[204:207], v147 offset:55296
	ds_read_b128 v[220:223], v147 offset:56320
	global_load_lds_dwordx4 v[208:209], off
	v_lshl_add_u64 v[208:209], v[224:225], 0, s[96:97]
	s_add_i32 m0, s31, 0x2000
	s_add_i32 s31, s64, s47
	global_load_lds_dwordx4 v[208:209], off
	v_lshl_add_u64 v[208:209], v[230:231], 0, s[96:97]
	s_mov_b32 m0, s31
	s_nop 0
	global_load_lds_dwordx4 v[208:209], off
	v_lshl_add_u64 v[208:209], v[236:237], 0, s[96:97]
	s_add_i32 m0, s31, 0x2000
	s_nop 0
	global_load_lds_dwordx4 v[208:209], off
	v_lshl_add_u64 v[208:209], v[238:239], 0, s[96:97]
	s_mov_b32 m0, s57
	s_nop 0
	global_load_lds_dwordx4 v[208:209], off
	v_lshl_add_u64 v[208:209], v[240:241], 0, s[96:97]
	s_mov_b32 m0, s58
	s_nop 0
	global_load_lds_dwordx4 v[208:209], off
	s_nop 0
	s_nop 0
	s_nop 0
	s_nop 0
	s_nop 0
	s_waitcnt vmcnt(8)
	s_waitcnt lgkmcnt(0)
	s_barrier
	s_waitcnt lgkmcnt(0)
	v_mfma_f32_16x16x32_bf16 v[62:65], v[148:151], v[180:183], v[62:65]
	v_mfma_f32_16x16x32_bf16 v[58:61], v[156:159], v[180:183], v[58:61]
	v_mfma_f32_16x16x32_bf16 v[46:49], v[148:151], v[188:191], v[46:49]
	v_mfma_f32_16x16x32_bf16 v[42:45], v[156:159], v[188:191], v[42:45]
	v_mfma_f32_16x16x32_bf16 v[30:33], v[148:151], v[196:199], v[30:33]
	v_mfma_f32_16x16x32_bf16 v[26:29], v[156:159], v[196:199], v[26:29]
	v_mfma_f32_16x16x32_bf16 v[14:17], v[148:151], v[204:207], v[14:17]
	v_mfma_f32_16x16x32_bf16 v[10:13], v[156:159], v[204:207], v[10:13]
	v_mfma_f32_16x16x32_bf16 v[62:65], v[152:155], v[184:187], v[62:65]
	v_mfma_f32_16x16x32_bf16 v[58:61], v[160:163], v[184:187], v[58:61]
	v_mfma_f32_16x16x32_bf16 v[46:49], v[152:155], v[192:195], v[46:49]
	v_mfma_f32_16x16x32_bf16 v[42:45], v[160:163], v[192:195], v[42:45]
	v_mfma_f32_16x16x32_bf16 v[30:33], v[152:155], v[200:203], v[30:33]
	v_mfma_f32_16x16x32_bf16 v[26:29], v[160:163], v[200:203], v[26:29]
	v_mfma_f32_16x16x32_bf16 v[14:17], v[152:155], v[220:223], v[14:17]
	v_mfma_f32_16x16x32_bf16 v[10:13], v[160:163], v[220:223], v[10:13]
	v_mfma_f32_16x16x32_bf16 v[54:57], v[164:167], v[180:183], v[54:57]
	v_mfma_f32_16x16x32_bf16 v[50:53], v[172:175], v[180:183], v[50:53]
	v_mfma_f32_16x16x32_bf16 v[38:41], v[164:167], v[188:191], v[38:41]
	v_mfma_f32_16x16x32_bf16 v[34:37], v[172:175], v[188:191], v[34:37]
	v_mfma_f32_16x16x32_bf16 v[22:25], v[164:167], v[196:199], v[22:25]
	v_mfma_f32_16x16x32_bf16 v[18:21], v[172:175], v[196:199], v[18:21]
	v_mfma_f32_16x16x32_bf16 v[6:9], v[164:167], v[204:207], v[6:9]
	v_mfma_f32_16x16x32_bf16 v[2:5], v[172:175], v[204:207], v[2:5]
	v_mfma_f32_16x16x32_bf16 v[54:57], v[168:171], v[184:187], v[54:57]
	v_mfma_f32_16x16x32_bf16 v[50:53], v[176:179], v[184:187], v[50:53]
	v_mfma_f32_16x16x32_bf16 v[38:41], v[168:171], v[192:195], v[38:41]
	v_mfma_f32_16x16x32_bf16 v[34:37], v[176:179], v[192:195], v[34:37]
	v_mfma_f32_16x16x32_bf16 v[22:25], v[168:171], v[200:203], v[22:25]
	v_mfma_f32_16x16x32_bf16 v[18:21], v[176:179], v[200:203], v[18:21]
	v_mfma_f32_16x16x32_bf16 v[6:9], v[168:171], v[220:223], v[6:9]
	v_mfma_f32_16x16x32_bf16 v[2:5], v[176:179], v[220:223], v[2:5]
	s_barrier
	s_add_u32 s36, s36, 0x100
	s_addc_u32 s37, s37, 0
	v_lshl_add_u64 v[144:145], v[144:145], 0, s[2:3]
	v_lshl_add_u64 v[142:143], v[142:143], 0, s[2:3]
	s_cmp_ge_u32 s63, s56
	s_mov_b32 s31, s63
	s_cbranch_scc0 .LBB0_476
	s_and_b64 vcc, exec, s[6:7]
	s_cbranch_vccnz .LBB0_464
	v_mov_b32_e32 v2, 0
	s_mov_b32 s55, s61
	s_mov_b32 s50, s62
	s_mov_b64 s[26:27], s[34:35]
	s_mov_b64 s[28:29], s[8:9]
	s_mov_b32 s60, s30
	v_mov_b32_e32 v3, v2
	v_mov_b32_e32 v4, v2
	v_mov_b32_e32 v5, v2
	v_mov_b32_e32 v6, v2
	v_mov_b32_e32 v7, v2
	v_mov_b32_e32 v8, v2
	v_mov_b32_e32 v9, v2
	v_mov_b32_e32 v18, v2
	v_mov_b32_e32 v19, v2
	v_mov_b32_e32 v20, v2
	v_mov_b32_e32 v21, v2
	v_mov_b32_e32 v22, v2
	v_mov_b32_e32 v23, v2
	v_mov_b32_e32 v24, v2
	v_mov_b32_e32 v25, v2
	v_mov_b32_e32 v34, v2
	v_mov_b32_e32 v35, v2
	v_mov_b32_e32 v36, v2
	v_mov_b32_e32 v37, v2
	v_mov_b32_e32 v38, v2
	v_mov_b32_e32 v39, v2
	v_mov_b32_e32 v40, v2
	v_mov_b32_e32 v41, v2
	v_mov_b32_e32 v50, v2
	v_mov_b32_e32 v51, v2
	v_mov_b32_e32 v52, v2
	v_mov_b32_e32 v53, v2
	v_mov_b32_e32 v54, v2
	v_mov_b32_e32 v55, v2
	v_mov_b32_e32 v56, v2
	v_mov_b32_e32 v57, v2
	v_mov_b32_e32 v10, v2
	v_mov_b32_e32 v11, v2
	v_mov_b32_e32 v12, v2
	v_mov_b32_e32 v13, v2
	v_mov_b32_e32 v14, v2
	v_mov_b32_e32 v15, v2
	v_mov_b32_e32 v16, v2
	v_mov_b32_e32 v17, v2
	v_mov_b32_e32 v26, v2
	v_mov_b32_e32 v27, v2
	v_mov_b32_e32 v28, v2
	v_mov_b32_e32 v29, v2
	v_mov_b32_e32 v30, v2
	v_mov_b32_e32 v31, v2
	v_mov_b32_e32 v32, v2
	v_mov_b32_e32 v33, v2
	v_mov_b32_e32 v42, v2
	v_mov_b32_e32 v43, v2
	v_mov_b32_e32 v44, v2
	v_mov_b32_e32 v45, v2
	v_mov_b32_e32 v46, v2
	v_mov_b32_e32 v47, v2
	v_mov_b32_e32 v48, v2
	v_mov_b32_e32 v49, v2
	v_mov_b32_e32 v58, v2
	v_mov_b32_e32 v59, v2
	v_mov_b32_e32 v60, v2
	v_mov_b32_e32 v61, v2
	v_mov_b32_e32 v62, v2
	v_mov_b32_e32 v63, v2
	v_mov_b32_e32 v64, v2
	v_mov_b32_e32 v65, v2
	v_mov_b32_e32 v66, v2
	v_mov_b32_e32 v67, v2
	v_mov_b32_e32 v68, v2
	v_mov_b32_e32 v69, v2
	v_mov_b32_e32 v70, v2
	v_mov_b32_e32 v71, v2
	v_mov_b32_e32 v72, v2
	v_mov_b32_e32 v73, v2
	v_mov_b32_e32 v82, v2
	v_mov_b32_e32 v83, v2
	v_mov_b32_e32 v84, v2
	v_mov_b32_e32 v85, v2
	v_mov_b32_e32 v86, v2
	v_mov_b32_e32 v87, v2
	v_mov_b32_e32 v88, v2
	v_mov_b32_e32 v89, v2
	v_mov_b32_e32 v98, v2
	v_mov_b32_e32 v99, v2
	v_mov_b32_e32 v100, v2
	v_mov_b32_e32 v101, v2
	v_mov_b32_e32 v102, v2
	v_mov_b32_e32 v103, v2
	v_mov_b32_e32 v104, v2
	v_mov_b32_e32 v105, v2
	v_mov_b32_e32 v114, v2
	v_mov_b32_e32 v115, v2
	v_mov_b32_e32 v116, v2
	v_mov_b32_e32 v117, v2
	v_mov_b32_e32 v118, v2
	v_mov_b32_e32 v119, v2
	v_mov_b32_e32 v120, v2
	v_mov_b32_e32 v121, v2
	v_mov_b32_e32 v74, v2
	v_mov_b32_e32 v75, v2
	v_mov_b32_e32 v76, v2
	v_mov_b32_e32 v77, v2
	v_mov_b32_e32 v78, v2
	v_mov_b32_e32 v79, v2
	v_mov_b32_e32 v80, v2
	v_mov_b32_e32 v81, v2
	v_mov_b32_e32 v90, v2
	v_mov_b32_e32 v91, v2
	v_mov_b32_e32 v92, v2
	v_mov_b32_e32 v93, v2
	v_mov_b32_e32 v94, v2
	v_mov_b32_e32 v95, v2
	v_mov_b32_e32 v96, v2
	v_mov_b32_e32 v97, v2
	v_mov_b32_e32 v106, v2
	v_mov_b32_e32 v107, v2
	v_mov_b32_e32 v108, v2
	v_mov_b32_e32 v109, v2
	v_mov_b32_e32 v110, v2
	v_mov_b32_e32 v111, v2
	v_mov_b32_e32 v112, v2
	v_mov_b32_e32 v113, v2
	v_mov_b32_e32 v122, v2
	v_mov_b32_e32 v123, v2
	v_mov_b32_e32 v124, v2
	v_mov_b32_e32 v125, v2
	v_mov_b32_e32 v126, v2
	v_mov_b32_e32 v127, v2
	v_mov_b32_e32 v128, v2
	v_mov_b32_e32 v129, v2
	s_branch .LBB0_464

.LBB0_643:
	s_waitcnt vmcnt(8)
	v_cvt_f32_u32_e32 v146, v146
	v_cvt_f32_u32_e32 v147, v147
	v_cvt_f32_u32_e32 v143, v143
	v_cvt_f32_u32_e32 v142, v142
	v_fmamk_f32 v146, v146, 0x34800000, v228
	v_cvt_f32_u32_e32 v149, v149
	v_rsq_f32_e32 v146, v146
	v_fmamk_f32 v147, v147, 0x34800000, v228
	v_fmamk_f32 v143, v143, 0x34800000, v228
	v_fmamk_f32 v142, v142, 0x34800000, v228
	v_cvt_f32_u32_e32 v150, v148
	v_fmamk_f32 v148, v149, 0x34800000, v228
	v_pk_mul_f32 v[104:105], v[146:147], v[104:105] op_sel_hi:[0,1]
	v_pk_mul_f32 v[102:103], v[146:147], v[102:103] op_sel_hi:[0,1]
	v_pk_mul_f32 v[100:101], v[146:147], v[100:101] op_sel_hi:[0,1]
	v_pk_mul_f32 v[98:99], v[146:147], v[98:99] op_sel_hi:[0,1]
	v_cvt_f32_u32_e32 v145, v145
	v_pk_mul_f32 v[72:73], v[146:147], v[72:73] op_sel_hi:[0,1]
	v_pk_mul_f32 v[70:71], v[146:147], v[70:71] op_sel_hi:[0,1]
	v_pk_mul_f32 v[68:69], v[146:147], v[68:69] op_sel_hi:[0,1]
	v_pk_mul_f32 v[66:67], v[146:147], v[66:67] op_sel_hi:[0,1]
	v_rsq_f32_e32 v146, v143
	v_rsq_f32_e32 v142, v142
	v_cvt_f32_u32_e32 v143, v144
	v_rsq_f32_e32 v148, v148
	v_fmamk_f32 v149, v150, 0x34800000, v228
	v_fmamk_f32 v145, v145, 0x34800000, v228
	v_pk_mul_f32 v[48:49], v[142:143], v[48:49] op_sel_hi:[0,1]
	v_fmamk_f32 v143, v143, 0x34800000, v228
	v_pk_mul_f32 v[128:129], v[148:149], v[128:129] op_sel_hi:[0,1]
	v_pk_mul_f32 v[126:127], v[148:149], v[126:127] op_sel_hi:[0,1]
	v_pk_mul_f32 v[124:125], v[148:149], v[124:125] op_sel_hi:[0,1]
	v_pk_mul_f32 v[122:123], v[148:149], v[122:123] op_sel_hi:[0,1]
	v_pk_mul_f32 v[96:97], v[148:149], v[96:97] op_sel_hi:[0,1]
	v_pk_mul_f32 v[94:95], v[148:149], v[94:95] op_sel_hi:[0,1]
	v_pk_mul_f32 v[92:93], v[148:149], v[92:93] op_sel_hi:[0,1]
	v_pk_mul_f32 v[90:91], v[148:149], v[90:91] op_sel_hi:[0,1]
	v_rsq_f32_e32 v148, v145
	v_rsq_f32_e32 v144, v143
	v_rsq_f32_e32 v150, v149
	v_rsq_f32_e32 v164, v147
	v_pk_mul_f32 v[46:47], v[142:143], v[46:47] op_sel_hi:[0,1]
	v_pk_mul_f32 v[44:45], v[142:143], v[44:45] op_sel_hi:[0,1]
	v_pk_mul_f32 v[42:43], v[142:143], v[42:43] op_sel_hi:[0,1]
	v_pk_mul_f32 v[16:17], v[142:143], v[16:17] op_sel_hi:[0,1]
	v_pk_mul_f32 v[14:15], v[142:143], v[14:15] op_sel_hi:[0,1]
	v_pk_mul_f32 v[12:13], v[142:143], v[12:13] op_sel_hi:[0,1]
	v_pk_mul_f32 v[10:11], v[142:143], v[10:11] op_sel_hi:[0,1]
	v_lshl_add_u32 v142, s18, 8, v1
	v_pk_mul_f32 v[64:65], v[148:149], v[64:65] op_sel_hi:[0,1]
	v_pk_mul_f32 v[62:63], v[148:149], v[62:63] op_sel_hi:[0,1]
	v_pk_mul_f32 v[60:61], v[148:149], v[60:61] op_sel_hi:[0,1]
	v_pk_mul_f32 v[58:59], v[148:149], v[58:59] op_sel_hi:[0,1]
	v_pk_mul_f32 v[56:57], v[146:147], v[56:57] op_sel_hi:[0,1]
	v_pk_mul_f32 v[54:55], v[146:147], v[54:55] op_sel_hi:[0,1]
	v_pk_mul_f32 v[52:53], v[146:147], v[52:53] op_sel_hi:[0,1]
	v_pk_mul_f32 v[50:51], v[146:147], v[50:51] op_sel_hi:[0,1]
	v_pk_mul_f32 v[40:41], v[144:145], v[40:41] op_sel_hi:[0,1]
	v_pk_mul_f32 v[38:39], v[144:145], v[38:39] op_sel_hi:[0,1]
	v_pk_mul_f32 v[36:37], v[144:145], v[36:37] op_sel_hi:[0,1]
	v_pk_mul_f32 v[34:35], v[144:145], v[34:35] op_sel_hi:[0,1]
	v_pk_mul_f32 v[32:33], v[148:149], v[32:33] op_sel_hi:[0,1]
	v_pk_mul_f32 v[30:31], v[148:149], v[30:31] op_sel_hi:[0,1]
	v_pk_mul_f32 v[28:29], v[148:149], v[28:29] op_sel_hi:[0,1]
	v_pk_mul_f32 v[26:27], v[148:149], v[26:27] op_sel_hi:[0,1]
	v_pk_mul_f32 v[24:25], v[146:147], v[24:25] op_sel_hi:[0,1]
	v_pk_mul_f32 v[22:23], v[146:147], v[22:23] op_sel_hi:[0,1]
	v_pk_mul_f32 v[20:21], v[146:147], v[20:21] op_sel_hi:[0,1]
	v_pk_mul_f32 v[18:19], v[146:147], v[18:19] op_sel_hi:[0,1]
	v_pk_mul_f32 v[8:9], v[144:145], v[8:9] op_sel_hi:[0,1]
	v_pk_mul_f32 v[6:7], v[144:145], v[6:7] op_sel_hi:[0,1]
	v_pk_mul_f32 v[4:5], v[144:145], v[4:5] op_sel_hi:[0,1]
	v_pk_mul_f32 v[2:3], v[144:145], v[2:3] op_sel_hi:[0,1]
	v_ashrrev_i32_e32 v143, 31, v142
	v_or_b32_e32 v148, 16, v142
	v_or_b32_e32 v146, 32, v142
	v_or_b32_e32 v144, 48, v142
	v_pk_mul_f32 v[120:121], v[150:151], v[120:121] op_sel_hi:[0,1]
	v_pk_mul_f32 v[118:119], v[150:151], v[118:119] op_sel_hi:[0,1]
	v_pk_mul_f32 v[116:117], v[150:151], v[116:117] op_sel_hi:[0,1]
	v_pk_mul_f32 v[114:115], v[150:151], v[114:115] op_sel_hi:[0,1]
	v_pk_mul_f32 v[112:113], v[164:165], v[112:113] op_sel_hi:[0,1]
	v_pk_mul_f32 v[110:111], v[164:165], v[110:111] op_sel_hi:[0,1]
	v_pk_mul_f32 v[108:109], v[164:165], v[108:109] op_sel_hi:[0,1]
	v_pk_mul_f32 v[106:107], v[164:165], v[106:107] op_sel_hi:[0,1]
	v_pk_mul_f32 v[88:89], v[150:151], v[88:89] op_sel_hi:[0,1]
	v_pk_mul_f32 v[86:87], v[150:151], v[86:87] op_sel_hi:[0,1]
	v_pk_mul_f32 v[84:85], v[150:151], v[84:85] op_sel_hi:[0,1]
	v_pk_mul_f32 v[82:83], v[150:151], v[82:83] op_sel_hi:[0,1]
	v_pk_mul_f32 v[80:81], v[164:165], v[80:81] op_sel_hi:[0,1]
	v_pk_mul_f32 v[78:79], v[164:165], v[78:79] op_sel_hi:[0,1]
	v_pk_mul_f32 v[76:77], v[164:165], v[76:77] op_sel_hi:[0,1]
	v_pk_mul_f32 v[74:75], v[164:165], v[74:75] op_sel_hi:[0,1]
	s_cmp_gt_i32 s40, 3
	v_lshlrev_b64 v[150:151], 11, v[142:143]
	s_mov_b64 s[18:19], -1
	v_ashrrev_i32_e32 v149, 31, v148
	v_ashrrev_i32_e32 v147, 31, v146
	v_ashrrev_i32_e32 v145, 31, v144
	s_cbranch_scc0 .LBB0_645
	v_lshl_add_u32 v164, s40, 7, v161
	v_mov_b32_e32 v165, v0
	v_lshl_add_u64 v[166:167], s[82:83], 0, v[150:151]
	v_lshlrev_b64 v[168:169], 1, v[164:165]
	v_pk_mul_f32 v[164:165], v[126:127], v[94:95]
	v_lshl_add_u64 v[170:171], v[166:167], 0, v[168:169]
	v_pk_mul_f32 v[166:167], v[128:129], v[96:97]
	v_cvt_pk_bf16_f32 v164, v164, v165
	v_pk_mul_f32 v[172:173], v[124:125], v[92:93]
	v_cvt_pk_bf16_f32 v165, v166, v167
	v_pk_mul_f32 v[174:175], v[122:123], v[90:91]
	v_pk_mul_f32 v[176:177], v[114:115], v[82:83]
	v_cvt_pk_bf16_f32 v166, v174, v175
	v_cvt_pk_bf16_f32 v167, v172, v173
	v_pk_mul_f32 v[174:175], v[116:117], v[84:85]
	global_store_dwordx4 v[170:171], v[164:167], off sc1
	s_nop 1
	v_lshlrev_b64 v[164:165], 11, v[148:149]
	v_lshl_add_u64 v[164:165], s[82:83], 0, v[164:165]
	v_lshl_add_u64 v[172:173], v[164:165], 0, v[168:169]
	v_pk_mul_f32 v[164:165], v[118:119], v[86:87]
	v_pk_mul_f32 v[166:167], v[120:121], v[88:89]
	v_cvt_pk_bf16_f32 v164, v164, v165
	s_nop 0
	v_cvt_pk_bf16_f32 v165, v166, v167
	v_cvt_pk_bf16_f32 v166, v176, v177
	v_cvt_pk_bf16_f32 v167, v174, v175
	v_pk_mul_f32 v[174:175], v[108:109], v[76:77]
	global_store_dwordx4 v[172:173], v[164:167], off sc1
	s_nop 1
	v_lshlrev_b64 v[164:165], 11, v[146:147]
	v_lshl_add_u64 v[164:165], s[82:83], 0, v[164:165]
	v_lshl_add_u64 v[172:173], v[164:165], 0, v[168:169]
	v_pk_mul_f32 v[164:165], v[110:111], v[78:79]
	v_pk_mul_f32 v[166:167], v[112:113], v[80:81]
	v_cvt_pk_bf16_f32 v164, v164, v165
	v_pk_mul_f32 v[176:177], v[106:107], v[74:75]
	v_cvt_pk_bf16_f32 v165, v166, v167
	s_nop 0
	v_cvt_pk_bf16_f32 v166, v176, v177
	v_cvt_pk_bf16_f32 v167, v174, v175
	v_pk_mul_f32 v[174:175], v[98:99], v[66:67]
	global_store_dwordx4 v[172:173], v[164:167], off sc1
	s_nop 1
	v_lshlrev_b64 v[164:165], 11, v[144:145]
	v_lshl_add_u64 v[164:165], s[82:83], 0, v[164:165]
	v_lshl_add_u64 v[168:169], v[164:165], 0, v[168:169]
	v_pk_mul_f32 v[166:167], v[104:105], v[72:73]
	v_pk_mul_f32 v[164:165], v[102:103], v[70:71]
	v_pk_mul_f32 v[172:173], v[100:101], v[68:69]
	v_cvt_pk_bf16_f32 v164, v164, v165
	v_cvt_pk_bf16_f32 v165, v166, v167
	v_cvt_pk_bf16_f32 v166, v174, v175
	v_pk_mul_f32 v[174:175], v[58:59], v[26:27]
	v_cvt_pk_bf16_f32 v167, v172, v173
	v_pk_mul_f32 v[172:173], v[60:61], v[28:29]
	global_store_dwordx4 v[168:169], v[164:167], off sc1
	s_nop 1
	v_pk_mul_f32 v[166:167], v[64:65], v[32:33]
	v_pk_mul_f32 v[164:165], v[62:63], v[30:31]
	v_lshl_add_u64 v[168:169], v[170:171], 0, s[76:77]
	v_cvt_pk_bf16_f32 v164, v164, v165
	v_cvt_pk_bf16_f32 v165, v166, v167
	v_cvt_pk_bf16_f32 v166, v174, v175
	v_cvt_pk_bf16_f32 v167, v172, v173
	v_pk_mul_f32 v[172:173], v[52:53], v[20:21]
	global_store_dwordx4 v[168:169], v[164:167], off sc1
	s_nop 1
	v_pk_mul_f32 v[166:167], v[56:57], v[24:25]
	v_pk_mul_f32 v[164:165], v[54:55], v[22:23]
	v_pk_mul_f32 v[174:175], v[50:51], v[18:19]
	v_cvt_pk_bf16_f32 v164, v164, v165
	v_cvt_pk_bf16_f32 v165, v166, v167
	v_lshl_add_u64 v[168:169], v[170:171], 0, s[72:73]
	v_cvt_pk_bf16_f32 v166, v174, v175
	v_cvt_pk_bf16_f32 v167, v172, v173
	v_pk_mul_f32 v[172:173], v[44:45], v[12:13]
	global_store_dwordx4 v[168:169], v[164:167], off sc1
	s_nop 1
	v_pk_mul_f32 v[166:167], v[48:49], v[16:17]
	v_pk_mul_f32 v[164:165], v[46:47], v[14:15]
	v_pk_mul_f32 v[174:175], v[42:43], v[10:11]
	v_cvt_pk_bf16_f32 v164, v164, v165
	v_cvt_pk_bf16_f32 v165, v166, v167
	v_lshl_add_u64 v[168:169], v[170:171], 0, s[92:93]
	v_cvt_pk_bf16_f32 v166, v174, v175
	v_cvt_pk_bf16_f32 v167, v172, v173
	v_pk_mul_f32 v[172:173], v[34:35], v[2:3]
	global_store_dwordx4 v[168:169], v[164:167], off sc1
	s_nop 1
	v_pk_mul_f32 v[166:167], v[40:41], v[8:9]
	v_pk_mul_f32 v[164:165], v[38:39], v[6:7]
	v_lshl_add_u64 v[168:169], v[170:171], 0, s[50:51]
	v_pk_mul_f32 v[170:171], v[36:37], v[4:5]
	v_cvt_pk_bf16_f32 v164, v164, v165
	v_cvt_pk_bf16_f32 v165, v166, v167
	v_cvt_pk_bf16_f32 v166, v172, v173
	s_nop 0
	v_cvt_pk_bf16_f32 v167, v170, v171
	s_nop 0
	global_store_dwordx4 v[168:169], v[164:167], off sc1
	s_nop 1
	s_cbranch_execnz .LBB0_647
	s_branch .LBB0_646
